# scan wave priorities: token loops at s_setprio 2, prep at 0 (was prep 3 / loop 0)
# baseline (speedup 1.0000x reference)
.LBB0_344:
	s_add_i32 s24, s12, -7
	s_and_b64 s[16:17], s[2:3], exec
	s_cselect_b32 s12, s12, s24
	s_add_i32 s16, s12, -1
	s_max_i32 s16, s16, s23
	s_min_i32 s16, s16, s22
	s_mulk_i32 s16, 0x1800
	s_add_u32 s16, s88, s16
	s_addc_u32 s17, s89, 0
	global_load_ushort v163, v223, s[16:17] offset:1536
	global_load_ushort v157, v223, s[16:17] offset:3072
	global_load_ushort v139, v224, s[16:17]
	global_load_ushort v130, v225, s[16:17]
	s_max_i32 s16, s12, s23
	s_min_i32 s16, s16, s22
	s_mulk_i32 s16, 0x1800
	s_add_u32 s16, s88, s16
	s_addc_u32 s17, s89, 0
	global_load_ushort v164, v223, s[16:17] offset:1536
	global_load_ushort v160, v223, s[16:17] offset:3072
	global_load_ushort v140, v224, s[16:17]
	global_load_ushort v131, v225, s[16:17]
	s_add_i32 s16, s12, 1
	s_max_i32 s16, s16, s23
	s_min_i32 s16, s16, s22
	s_mulk_i32 s16, 0x1800
	s_add_u32 s16, s88, s16
	s_addc_u32 s17, s89, 0
	global_load_ushort v165, v223, s[16:17] offset:1536
	global_load_ushort v162, v223, s[16:17] offset:3072
	global_load_ushort v142, v224, s[16:17]
	global_load_ushort v132, v225, s[16:17]
	s_add_i32 s16, s12, 2
	s_max_i32 s16, s16, s23
	s_min_i32 s16, s16, s22
	s_mulk_i32 s16, 0x1800
	s_add_u32 s16, s88, s16
	s_addc_u32 s17, s89, 0
	global_load_ushort v166, v223, s[16:17] offset:1536
	global_load_ushort v150, v223, s[16:17] offset:3072
	global_load_ushort v144, v224, s[16:17]
	global_load_ushort v133, v225, s[16:17]
	s_add_i32 s16, s12, 3
	s_max_i32 s16, s16, s23
	s_min_i32 s16, s16, s22
	s_mulk_i32 s16, 0x1800
	s_add_u32 s16, s88, s16
	s_addc_u32 s17, s89, 0
	global_load_ushort v167, v223, s[16:17] offset:1536
	global_load_ushort v151, v223, s[16:17] offset:3072
	global_load_ushort v143, v224, s[16:17]
	global_load_ushort v134, v225, s[16:17]
	s_add_i32 s16, s12, 4
	s_max_i32 s16, s16, s23
	s_min_i32 s16, s16, s22
	s_mulk_i32 s16, 0x1800
	s_add_u32 s16, s88, s16
	s_addc_u32 s17, s89, 0
	global_load_ushort v168, v223, s[16:17] offset:1536
	global_load_ushort v152, v223, s[16:17] offset:3072
	global_load_ushort v145, v224, s[16:17]
	global_load_ushort v135, v225, s[16:17]
	s_add_i32 s16, s12, 5
	s_max_i32 s16, s16, s23
	s_min_i32 s16, s16, s22
	s_mulk_i32 s16, 0x1800
	s_add_u32 s16, s88, s16
	s_addc_u32 s17, s89, 0
	global_load_ushort v169, v223, s[16:17] offset:1536
	global_load_ushort v153, v223, s[16:17] offset:3072
	global_load_ushort v146, v224, s[16:17]
	global_load_ushort v136, v225, s[16:17]
	s_add_i32 s16, s12, 6
	s_max_i32 s16, s16, s23
	s_min_i32 s16, s16, s22
	s_mulk_i32 s16, 0x1800
	s_add_u32 s16, s88, s16
	s_addc_u32 s17, s89, 0
	global_load_ushort v237, v223, s[16:17] offset:1536
	global_load_ushort v154, v223, s[16:17] offset:3072
	global_load_ushort v148, v224, s[16:17]
	global_load_ushort v137, v225, s[16:17]
	s_add_i32 s16, s12, 7
	s_max_i32 s16, s16, s23
	s_min_i32 s16, s16, s22
	s_mulk_i32 s16, 0x1800
	s_add_u32 s16, s88, s16
	s_addc_u32 s17, s89, 0
	s_add_i32 s12, s12, 8
	s_max_i32 s12, s12, s23
	s_min_i32 s12, s12, s22
	s_mulk_i32 s12, 0x1800
	global_load_ushort v238, v223, s[16:17] offset:1536
	global_load_ushort v155, v223, s[16:17] offset:3072
	global_load_ushort v147, v224, s[16:17]
	global_load_ushort v138, v225, s[16:17]
	s_add_u32 s16, s88, s12
	s_addc_u32 s17, s89, 0
	global_load_ushort v239, v223, s[16:17] offset:1536
	global_load_ushort v156, v223, s[16:17] offset:3072
	global_load_ushort v149, v224, s[16:17]
	global_load_ushort v141, v225, s[16:17]
	s_setprio 0
	s_mov_b64 s[16:17], -1
	s_and_b64 vcc, exec, s[14:15]
	s_cbranch_vccz .LBB0_350
	s_and_b64 vcc, exec, s[4:5]
	s_mov_b64 s[14:15], -1
	s_cbranch_vccnz .LBB0_347
	s_sub_i32 s12, 0x40ff, s21
	s_mov_b64 s[14:15], 0

.LBB0_352:
	s_add_i32 s16, s12, -7
	s_and_b64 s[14:15], s[2:3], exec
	s_cselect_b32 s14, s12, s16
	s_cmp_gt_i32 s14, s23
	ds_read_b32 v240, v170
	ds_read_b32 v241, v171
	s_waitcnt vmcnt(49)
	v_lshlrev_b32_e32 v236, 16, v236
	s_cselect_b64 vcc, -1, 0
	s_waitcnt vmcnt(48)
	v_lshlrev_b32_e32 v233, 16, v233
	v_cndmask_b32_e32 v236, 0, v236, vcc
	s_waitcnt vmcnt(47)
	v_lshlrev_b32_e32 v235, 16, v235
	v_sub_f32_e32 v236, v236, v233
	v_sub_f32_e32 v242, v235, v233
	s_waitcnt lgkmcnt(1)
	v_fma_f32 v236, v240, v236, v233
	s_waitcnt lgkmcnt(0)
	v_fmac_f32_e32 v236, v242, v241
	s_waitcnt vmcnt(46)
	v_lshlrev_b32_e32 v232, 16, v232
	v_sub_f32_e32 v233, v233, v235
	ds_write_b32 v172, v236 offset:1024
	v_sub_f32_e32 v236, v232, v235
	v_fma_f32 v233, v233, v240, v235
	v_fmac_f32_e32 v233, v236, v241
	s_waitcnt vmcnt(45)
	v_lshlrev_b32_e32 v230, 16, v230
	v_sub_f32_e32 v235, v235, v232
	ds_write_b32 v173, v233 offset:1024
	v_sub_f32_e32 v233, v230, v232
	v_fma_f32 v235, v235, v240, v232
	s_waitcnt vmcnt(44)
	v_lshlrev_b32_e32 v229, 16, v229
	v_sub_f32_e32 v232, v232, v230
	v_fmac_f32_e32 v235, v233, v241
	v_sub_f32_e32 v233, v229, v230
	v_fma_f32 v232, v232, v240, v230
	v_fmac_f32_e32 v232, v233, v241
	s_waitcnt vmcnt(43)
	v_lshlrev_b32_e32 v228, 16, v228
	v_sub_f32_e32 v230, v230, v229
	ds_write_b32 v174, v235 offset:1024
	ds_write_b32 v175, v232 offset:1024
	v_sub_f32_e32 v232, v228, v229
	v_fma_f32 v230, v230, v240, v229
	v_fmac_f32_e32 v230, v232, v241
	s_waitcnt vmcnt(42)
	v_lshlrev_b32_e32 v227, 16, v227
	v_sub_f32_e32 v229, v229, v228
	ds_write_b32 v176, v230 offset:1024
	v_sub_f32_e32 v230, v227, v228
	v_fma_f32 v229, v229, v240, v228
	v_fmac_f32_e32 v229, v230, v241
	ds_write_b32 v177, v229 offset:1024
	s_waitcnt vmcnt(41)
	v_lshlrev_b32_e32 v229, 16, v234
	v_sub_f32_e32 v228, v228, v227
	s_add_i32 s14, s14, 8
	v_sub_f32_e32 v230, v229, v227
	v_fma_f32 v228, v228, v240, v227
	s_cmp_gt_i32 s14, s22
	v_fmac_f32_e32 v228, v230, v241
	ds_write_b32 v178, v228 offset:1024
	s_waitcnt vmcnt(40)
	v_lshlrev_b32_e32 v228, 16, v231
	s_cselect_b64 s[14:15], -1, 0
	v_cndmask_b32_e64 v228, v228, 0, s[14:15]
	v_sub_f32_e32 v227, v227, v229
	v_sub_f32_e32 v228, v228, v229
	v_fmac_f32_e32 v229, v227, v240
	v_fmac_f32_e32 v229, v241, v228
	ds_write_b32 v179, v229 offset:1024
	ds_read_b32 v227, v170 offset:512
	ds_read_b32 v228, v180
	s_waitcnt vmcnt(39)
	v_lshlrev_b32_e32 v163, 16, v163
	s_waitcnt vmcnt(35)
	v_lshlrev_b32_e32 v164, 16, v164
	v_cndmask_b32_e32 v163, 0, v163, vcc
	s_waitcnt vmcnt(31)
	v_lshlrev_b32_e32 v165, 16, v165
	v_sub_f32_e32 v163, v163, v164
	v_sub_f32_e32 v229, v165, v164
	s_waitcnt lgkmcnt(1)
	v_fma_f32 v163, v163, v227, v164
	s_waitcnt lgkmcnt(0)
	v_fmac_f32_e32 v163, v229, v228
	ds_write_b32 v172, v163 offset:512
	s_waitcnt vmcnt(27)
	v_lshlrev_b32_e32 v163, 16, v166
	v_sub_f32_e32 v164, v164, v165
	v_sub_f32_e32 v166, v163, v165
	v_fma_f32 v164, v164, v227, v165
	v_fmac_f32_e32 v164, v166, v228
	ds_write_b32 v173, v164 offset:512
	s_waitcnt vmcnt(23)
	v_lshlrev_b32_e32 v164, 16, v167
	v_sub_f32_e32 v165, v165, v163
	v_sub_f32_e32 v166, v164, v163
	v_fma_f32 v165, v165, v227, v163
	v_fmac_f32_e32 v165, v166, v228
	ds_write_b32 v174, v165 offset:512
	s_waitcnt vmcnt(19)
	v_lshlrev_b32_e32 v165, 16, v168
	v_sub_f32_e32 v163, v163, v164
	v_sub_f32_e32 v166, v165, v164
	v_fma_f32 v163, v163, v227, v164
	v_fmac_f32_e32 v163, v166, v228
	ds_write_b32 v175, v163 offset:512
	s_waitcnt vmcnt(15)
	v_lshlrev_b32_e32 v163, 16, v169
	v_sub_f32_e32 v164, v164, v165
	v_sub_f32_e32 v166, v163, v165
	v_fma_f32 v164, v164, v227, v165
	v_fmac_f32_e32 v164, v166, v228
	ds_write_b32 v176, v164 offset:512
	s_waitcnt vmcnt(11)
	v_lshlrev_b32_e32 v164, 16, v237
	v_sub_f32_e32 v165, v165, v163
	v_sub_f32_e32 v166, v164, v163
	v_fma_f32 v165, v165, v227, v163
	v_fmac_f32_e32 v165, v166, v228
	ds_write_b32 v177, v165 offset:512
	s_waitcnt vmcnt(7)
	v_lshlrev_b32_e32 v165, 16, v238
	v_sub_f32_e32 v163, v163, v164
	v_sub_f32_e32 v166, v165, v164
	v_fma_f32 v163, v163, v227, v164
	v_fmac_f32_e32 v163, v166, v228
	ds_write_b32 v178, v163 offset:512
	s_waitcnt vmcnt(3)
	v_lshlrev_b32_e32 v163, 16, v239
	v_cndmask_b32_e64 v163, v163, 0, s[14:15]
	v_sub_f32_e32 v164, v164, v165
	v_sub_f32_e32 v163, v163, v165
	v_fmac_f32_e32 v165, v164, v227
	v_fmac_f32_e32 v165, v163, v228
	ds_write_b32 v179, v165 offset:512
	ds_read_b32 v163, v170 offset:1024
	ds_read_b32 v164, v181
	v_lshlrev_b32_e32 v157, 16, v157
	v_lshlrev_b32_e32 v160, 16, v160
	v_cndmask_b32_e32 v157, 0, v157, vcc
	v_lshlrev_b32_e32 v162, 16, v162
	v_sub_f32_e32 v157, v157, v160
	v_sub_f32_e32 v165, v162, v160
	s_waitcnt lgkmcnt(1)
	v_fma_f32 v157, v157, v163, v160
	s_waitcnt lgkmcnt(0)
	v_fmac_f32_e32 v157, v165, v164
	v_lshlrev_b32_e32 v150, 16, v150
	v_sub_f32_e32 v160, v160, v162
	ds_read_b32 v166, v191
	ds_read_b32 v167, v208
	ds_write_b32 v182, v157 offset:1280
	v_sub_f32_e32 v157, v150, v162
	v_fma_f32 v160, v160, v163, v162
	v_fmac_f32_e32 v160, v157, v164
	ds_write_b32 v183, v160 offset:1280
	v_lshlrev_b32_e32 v151, 16, v151
	v_sub_f32_e32 v160, v162, v150
	v_sub_f32_e32 v157, v151, v150
	v_fma_f32 v160, v160, v163, v150
	v_lshlrev_b32_e32 v152, 16, v152
	v_sub_f32_e32 v150, v150, v151
	v_fmac_f32_e32 v160, v157, v164
	v_sub_f32_e32 v157, v152, v151
	v_fma_f32 v150, v150, v163, v151
	v_fmac_f32_e32 v150, v157, v164
	ds_write_b32 v184, v160 offset:1280
	ds_write_b32 v185, v150 offset:1280
	v_lshlrev_b32_e32 v150, 16, v153
	v_sub_f32_e32 v151, v151, v152
	v_sub_f32_e32 v153, v150, v152
	v_fma_f32 v151, v151, v163, v152
	v_fmac_f32_e32 v151, v153, v164
	ds_write_b32 v186, v151 offset:1280
	v_lshlrev_b32_e32 v151, 16, v154
	v_sub_f32_e32 v152, v152, v150
	v_sub_f32_e32 v153, v151, v150
	v_fma_f32 v152, v152, v163, v150
	v_fmac_f32_e32 v152, v153, v164
	ds_write_b32 v187, v152 offset:1280
	v_lshlrev_b32_e32 v152, 16, v155
	v_sub_f32_e32 v150, v150, v151
	v_sub_f32_e32 v153, v152, v151
	v_fma_f32 v150, v150, v163, v151
	v_fmac_f32_e32 v150, v153, v164
	ds_write_b32 v189, v150 offset:1280
	s_waitcnt vmcnt(2)
	v_lshlrev_b32_e32 v150, 16, v156
	v_cndmask_b32_e64 v150, v150, 0, s[14:15]
	v_sub_f32_e32 v151, v151, v152
	v_sub_f32_e32 v150, v150, v152
	v_fmac_f32_e32 v152, v151, v163
	v_fmac_f32_e32 v152, v150, v164
	ds_write_b32 v190, v152 offset:1280
	ds_read2st64_b32 v[150:151], v170 offset0:6 offset1:8
	v_lshlrev_b32_e32 v139, 16, v139
	v_lshlrev_b32_e32 v140, 16, v140
	v_cndmask_b32_e32 v139, 0, v139, vcc
	v_lshlrev_b32_e32 v142, 16, v142
	v_sub_f32_e32 v139, v139, v140
	v_sub_f32_e32 v152, v142, v140
	s_waitcnt lgkmcnt(0)
	v_fma_f32 v139, v139, v150, v140
	v_fmac_f32_e32 v139, v152, v166
	v_add_f32_e32 v139, v139, v139
	v_mul_f32_e32 v139, 0x3fb8aa3b, v139
	v_lshlrev_b32_e32 v144, 16, v144
	v_sub_f32_e32 v140, v140, v142
	v_exp_f32_e32 v139, v139
	v_sub_f32_e32 v152, v144, v142
	v_fma_f32 v140, v140, v150, v142
	v_fmac_f32_e32 v140, v152, v166
	v_add_f32_e32 v140, v140, v140
	v_mul_f32_e32 v140, 0x3fb8aa3b, v140
	v_add_f32_e32 v139, 1.0, v139
	v_exp_f32_e32 v140, v140
	v_rcp_f32_e32 v139, v139
	v_sub_f32_e32 v142, v142, v144
	v_fma_f32 v142, v142, v150, v144
	v_add_f32_e32 v140, 1.0, v140
	v_fma_f32 v139, v139, -2.0, 1.0
	v_rcp_f32_e32 v140, v140
	v_bfe_u32 v152, v139, 16, 1
	v_add3_u32 v139, v139, v152, s19
	v_lshrrev_b32_e32 v139, 16, v139
	ds_write_b16 v192, v139 offset:12288
	ds_write_b16 v193, v139 offset:13440
	v_fma_f32 v139, v140, -2.0, 1.0
	v_bfe_u32 v140, v139, 16, 1
	v_add3_u32 v139, v139, v140, s19
	v_lshlrev_b32_e32 v140, 16, v143
	v_sub_f32_e32 v143, v140, v144
	v_fmac_f32_e32 v142, v143, v166
	v_add_f32_e32 v142, v142, v142
	v_mul_f32_e32 v142, 0x3fb8aa3b, v142
	v_exp_f32_e32 v142, v142
	v_lshrrev_b32_e32 v139, 16, v139
	ds_write_b16 v194, v139 offset:12288
	ds_write_b16 v195, v139 offset:13440
	v_sub_f32_e32 v144, v144, v140
	v_add_f32_e32 v139, 1.0, v142
	v_lshlrev_b32_e32 v142, 16, v145
	v_sub_f32_e32 v143, v142, v140
	v_fma_f32 v144, v144, v150, v140
	v_fmac_f32_e32 v144, v143, v166
	v_add_f32_e32 v143, v144, v144
	v_mul_f32_e32 v143, 0x3fb8aa3b, v143
	v_exp_f32_e32 v143, v143
	v_rcp_f32_e32 v139, v139
	v_sub_f32_e32 v140, v140, v142
	v_fma_f32 v140, v140, v150, v142
	v_add_f32_e32 v143, 1.0, v143
	v_fma_f32 v139, v139, -2.0, 1.0
	v_rcp_f32_e32 v143, v143
	v_bfe_u32 v144, v139, 16, 1
	v_add3_u32 v139, v139, v144, s19
	v_lshrrev_b32_e32 v139, 16, v139
	ds_write_b16 v196, v139 offset:12288
	ds_write_b16 v197, v139 offset:13440
	v_fma_f32 v139, v143, -2.0, 1.0
	v_bfe_u32 v143, v139, 16, 1
	v_add3_u32 v139, v139, v143, s19
	v_lshlrev_b32_e32 v143, 16, v146
	v_sub_f32_e32 v144, v143, v142
	v_fmac_f32_e32 v140, v144, v166
	v_add_f32_e32 v140, v140, v140
	v_mul_f32_e32 v140, 0x3fb8aa3b, v140
	v_exp_f32_e32 v140, v140
	v_lshrrev_b32_e32 v139, 16, v139
	ds_write_b16 v198, v139 offset:12288
	ds_write_b16 v199, v139 offset:13440
	v_sub_f32_e32 v142, v142, v143
	v_add_f32_e32 v139, 1.0, v140
	v_lshlrev_b32_e32 v140, 16, v148
	v_sub_f32_e32 v144, v140, v143
	v_fma_f32 v142, v142, v150, v143
	v_fmac_f32_e32 v142, v144, v166
	v_add_f32_e32 v142, v142, v142
	v_mul_f32_e32 v142, 0x3fb8aa3b, v142
	v_exp_f32_e32 v142, v142
	v_rcp_f32_e32 v139, v139
	v_sub_f32_e32 v143, v143, v140
	v_fma_f32 v143, v143, v150, v140
	v_add_f32_e32 v142, 1.0, v142
	v_fma_f32 v139, v139, -2.0, 1.0
	v_rcp_f32_e32 v142, v142
	v_bfe_u32 v144, v139, 16, 1
	v_add3_u32 v139, v139, v144, s19
	v_lshrrev_b32_e32 v139, 16, v139
	ds_write_b16 v200, v139 offset:12288
	ds_write_b16 v201, v139 offset:13440
	v_fma_f32 v139, v142, -2.0, 1.0
	v_bfe_u32 v142, v139, 16, 1
	v_add3_u32 v139, v139, v142, s19
	v_lshlrev_b32_e32 v142, 16, v147
	v_sub_f32_e32 v144, v142, v140
	v_fmac_f32_e32 v143, v144, v166
	v_add_f32_e32 v143, v143, v143
	v_mul_f32_e32 v143, 0x3fb8aa3b, v143
	v_exp_f32_e32 v143, v143
	v_lshrrev_b32_e32 v139, 16, v139
	ds_write_b16 v202, v139 offset:12288
	ds_write_b16 v203, v139 offset:13440
	v_sub_f32_e32 v140, v140, v142
	v_add_f32_e32 v139, 1.0, v143
	s_waitcnt vmcnt(1)
	v_lshlrev_b32_e32 v143, 16, v149
	v_cndmask_b32_e64 v143, v143, 0, s[14:15]
	v_sub_f32_e32 v143, v143, v142
	v_fmac_f32_e32 v142, v140, v150
	v_fmac_f32_e32 v142, v143, v166
	v_add_f32_e32 v140, v142, v142
	v_mul_f32_e32 v140, 0x3fb8aa3b, v140
	v_exp_f32_e32 v140, v140
	v_rcp_f32_e32 v139, v139
	v_lshlrev_b32_e32 v130, 16, v130
	v_lshlrev_b32_e32 v131, 16, v131
	v_add_f32_e32 v140, 1.0, v140
	v_fma_f32 v139, v139, -2.0, 1.0
	v_rcp_f32_e32 v140, v140
	v_bfe_u32 v142, v139, 16, 1
	v_add3_u32 v139, v139, v142, s19
	v_lshrrev_b32_e32 v139, 16, v139
	ds_write_b16 v204, v139 offset:12288
	ds_write_b16 v205, v139 offset:13440
	v_fma_f32 v139, v140, -2.0, 1.0
	v_bfe_u32 v140, v139, 16, 1
	v_add3_u32 v139, v139, v140, s19
	v_cndmask_b32_e32 v130, 0, v130, vcc
	v_lshrrev_b32_e32 v139, 16, v139
	v_lshlrev_b32_e32 v132, 16, v132
	v_sub_f32_e32 v130, v130, v131
	ds_write_b16 v206, v139 offset:12288
	ds_write_b16 v207, v139 offset:13440
	v_sub_f32_e32 v139, v132, v131
	v_fma_f32 v130, v130, v151, v131
	v_fmac_f32_e32 v130, v139, v167
	v_bfe_u32 v139, v130, 16, 1
	v_add3_u32 v130, v130, v139, s19
	v_lshrrev_b32_e32 v130, 16, v130
	ds_write_b16 v193, v130 offset:14592
	ds_write_b16 v193, v130 offset:15744
	v_lshlrev_b32_e32 v130, 16, v133
	v_sub_f32_e32 v131, v131, v132
	v_sub_f32_e32 v133, v130, v132
	v_fma_f32 v131, v131, v151, v132
	v_fmac_f32_e32 v131, v133, v167
	v_bfe_u32 v133, v131, 16, 1
	v_add3_u32 v131, v131, v133, s19
	v_lshrrev_b32_e32 v131, 16, v131
	ds_write_b16 v195, v131 offset:14592
	ds_write_b16 v195, v131 offset:15744
	v_lshlrev_b32_e32 v131, 16, v134
	v_sub_f32_e32 v132, v132, v130
	v_sub_f32_e32 v133, v131, v130
	v_fma_f32 v132, v132, v151, v130
	v_fmac_f32_e32 v132, v133, v167
	v_bfe_u32 v133, v132, 16, 1
	v_add3_u32 v132, v132, v133, s19
	v_lshrrev_b32_e32 v132, 16, v132
	ds_write_b16 v197, v132 offset:14592
	ds_write_b16 v197, v132 offset:15744
	v_lshlrev_b32_e32 v132, 16, v135
	v_sub_f32_e32 v130, v130, v131
	v_sub_f32_e32 v133, v132, v131
	v_fma_f32 v130, v130, v151, v131
	v_fmac_f32_e32 v130, v133, v167
	v_bfe_u32 v133, v130, 16, 1
	v_add3_u32 v130, v130, v133, s19
	v_lshrrev_b32_e32 v130, 16, v130
	ds_write_b16 v199, v130 offset:14592
	ds_write_b16 v199, v130 offset:15744
	v_lshlrev_b32_e32 v130, 16, v136
	v_sub_f32_e32 v131, v131, v132
	v_sub_f32_e32 v133, v130, v132
	v_fma_f32 v131, v131, v151, v132
	v_fmac_f32_e32 v131, v133, v167
	v_bfe_u32 v133, v131, 16, 1
	v_add3_u32 v131, v131, v133, s19
	v_lshrrev_b32_e32 v131, 16, v131
	ds_write_b16 v201, v131 offset:14592
	ds_write_b16 v201, v131 offset:15744
	v_lshlrev_b32_e32 v131, 16, v137
	v_sub_f32_e32 v132, v132, v130
	v_sub_f32_e32 v133, v131, v130
	v_fma_f32 v132, v132, v151, v130
	v_fmac_f32_e32 v132, v133, v167
	v_bfe_u32 v133, v132, 16, 1
	v_add3_u32 v132, v132, v133, s19
	v_lshrrev_b32_e32 v132, 16, v132
	ds_write_b16 v203, v132 offset:14592
	ds_write_b16 v203, v132 offset:15744
	v_lshlrev_b32_e32 v132, 16, v138
	v_sub_f32_e32 v130, v130, v131
	v_sub_f32_e32 v133, v132, v131
	v_fma_f32 v130, v130, v151, v131
	v_fmac_f32_e32 v130, v133, v167
	v_bfe_u32 v133, v130, 16, 1
	v_add3_u32 v130, v130, v133, s19
	v_lshrrev_b32_e32 v130, 16, v130
	ds_write_b16 v205, v130 offset:14592
	ds_write_b16 v205, v130 offset:15744
	s_waitcnt vmcnt(0)
	v_lshlrev_b32_e32 v130, 16, v141
	v_cndmask_b32_e64 v130, v130, 0, s[14:15]
	v_sub_f32_e32 v131, v131, v132
	v_sub_f32_e32 v130, v130, v132
	v_fmac_f32_e32 v132, v131, v151
	v_fmac_f32_e32 v132, v130, v167
	v_bfe_u32 v130, v132, 16, 1
	v_add3_u32 v130, v132, v130, s19
	v_lshrrev_b32_e32 v130, 16, v130
	ds_write_b16 v207, v130 offset:14592
	ds_write_b16 v207, v130 offset:15744
	s_and_saveexec_b64 s[14:15], s[6:7]
	v_add_u32_e32 v130, s12, v220
	ds_write_b32 v226, v130 offset:12416
	s_or_b64 exec, exec, s[14:15]
	ds_read_b128 v[130:133], v209 offset:12288
	ds_read_b128 v[134:137], v209 offset:14592
	ds_read_b128 v[138:141], v210
	ds_read_b128 v[142:145], v211
	ds_read_b128 v[146:149], v210 offset:2304
	ds_read_b128 v[150:153], v211 offset:2304
	ds_read_b128 v[154:157], v210 offset:4608
	ds_read_b128 v[162:165], v211 offset:4608
	ds_read_b128 v[166:169], v210 offset:6912
	ds_read_b128 v[228:231], v211 offset:6912
	s_waitcnt lgkmcnt(7)
	v_mfma_f32_16x16x32_bf16 v[138:141], v[130:133], v[138:141], 0
	s_waitcnt lgkmcnt(6)
	v_mfma_f32_16x16x32_bf16 v[142:145], v[134:137], v[142:145], 0
	s_waitcnt lgkmcnt(5)
	v_mfma_f32_16x16x32_bf16 v[146:149], v[130:133], v[146:149], 0
	s_waitcnt lgkmcnt(4)
	v_mfma_f32_16x16x32_bf16 v[150:153], v[134:137], v[150:153], 0
	s_waitcnt lgkmcnt(3)
	v_mfma_f32_16x16x32_bf16 v[154:157], v[130:133], v[154:157], 0
	s_waitcnt lgkmcnt(2)
	v_mfma_f32_16x16x32_bf16 v[162:165], v[134:137], v[162:165], 0
	s_waitcnt lgkmcnt(1)
	v_mfma_f32_16x16x32_bf16 v[130:133], v[130:133], v[166:169], 0
	s_waitcnt lgkmcnt(0)
	v_mfma_f32_16x16x32_bf16 v[134:137], v[134:137], v[228:231], 0
	ds_read_b128 v[166:169], v209 offset:12352
	ds_read_b128 v[228:231], v209 offset:14656
	ds_read_b128 v[232:235], v210 offset:64
	ds_read_b128 v[236:239], v211 offset:64
	s_waitcnt lgkmcnt(1)
	v_mfma_f32_16x16x32_bf16 v[138:141], v[166:169], v[232:235], v[138:141]
	s_waitcnt lgkmcnt(0)
	v_mfma_f32_16x16x32_bf16 v[142:145], v[228:231], v[236:239], v[142:145]
	ds_read_b128 v[232:235], v210 offset:2368
	ds_read_b128 v[236:239], v211 offset:2368
	s_waitcnt lgkmcnt(1)
	v_mfma_f32_16x16x32_bf16 v[146:149], v[166:169], v[232:235], v[146:149]
	s_waitcnt lgkmcnt(0)
	v_mfma_f32_16x16x32_bf16 v[150:153], v[228:231], v[236:239], v[150:153]
	ds_read_b128 v[232:235], v210 offset:4672
	ds_read_b128 v[236:239], v211 offset:4672
	s_waitcnt lgkmcnt(1)
	v_mfma_f32_16x16x32_bf16 v[154:157], v[166:169], v[232:235], v[154:157]
	s_waitcnt lgkmcnt(0)
	v_mfma_f32_16x16x32_bf16 v[162:165], v[228:231], v[236:239], v[162:165]
	ds_read_b128 v[232:235], v210 offset:6976
	ds_read_b128 v[236:239], v211 offset:6976
	s_nop 3
	v_cndmask_b32_e64 v157, v141, v157, s[8:9]
	v_cndmask_b32_e64 v156, v140, v156, s[8:9]
	s_waitcnt lgkmcnt(1)
	v_mfma_f32_16x16x32_bf16 v[130:133], v[166:169], v[232:235], v[130:133]
	v_cndmask_b32_e64 v155, v139, v155, s[8:9]
	v_cndmask_b32_e64 v154, v138, v154, s[8:9]
	v_cndmask_b32_e64 v145, v145, v165, s[8:9]
	s_waitcnt lgkmcnt(0)
	v_mfma_f32_16x16x32_bf16 v[134:137], v[228:231], v[236:239], v[134:137]
	s_nop 2
	v_cndmask_b32_e64 v149, v149, v133, s[8:9]
	v_cndmask_b32_e64 v148, v148, v132, s[8:9]
	v_cndmask_b32_e64 v147, v147, v131, s[8:9]
	v_cndmask_b32_e64 v146, v146, v130, s[8:9]
	v_cndmask_b32_e64 v144, v144, v164, s[8:9]
	v_cndmask_b32_e64 v143, v143, v163, s[8:9]
	v_cndmask_b32_e64 v142, v142, v162, s[8:9]
	v_cndmask_b32_e64 v153, v153, v137, s[8:9]
	v_cndmask_b32_e64 v152, v152, v136, s[8:9]
	v_cndmask_b32_e64 v151, v151, v135, s[8:9]
	v_cndmask_b32_e64 v150, v150, v134, s[8:9]
	ds_read_b64 v[130:131], v217 offset:512
	ds_read_b64 v[132:133], v214
	ds_read_b64 v[134:135], v212
	ds_read_b64 v[136:137], v213
	ds_read_b64 v[138:139], v215
	s_waitcnt lgkmcnt(3)
	v_pk_mul_f32 v[132:133], v[132:133], v[130:131]
	s_nop 0
	v_pk_mul_f32 v[140:141], v[132:133], v[132:133]
	s_waitcnt lgkmcnt(2)
	v_add_f32_e32 v134, v154, v134
	v_add_f32_e32 v140, v140, v141
	v_add_f32_e32 v135, v146, v135
	v_mul_f32_e32 v134, 0xbfb8aa3b, v134
	v_add_f32_dpp v140, v140, v140 quad_perm:[1,0,3,2] row_mask:0xf bank_mask:0xf bound_ctrl:1
	v_mul_f32_e32 v135, 0xbfb8aa3b, v135
	v_exp_f32_e32 v134, v134
	v_add_f32_dpp v140, v140, v140 quad_perm:[2,3,0,1] row_mask:0xf bank_mask:0xf bound_ctrl:1
	v_exp_f32_e32 v135, v135
	s_waitcnt lgkmcnt(1)
	v_add_f32_e32 v137, v150, v137
	v_add_f32_dpp v140, v140, v140 row_ror:4 row_mask:0xf bank_mask:0xf bound_ctrl:1
	v_add_f32_e32 v134, 1.0, v134
	v_add_f32_e32 v135, 1.0, v135
	v_add_f32_dpp v140, v140, v140 row_ror:8 row_mask:0xf bank_mask:0xf bound_ctrl:1
	ds_bpermute_b32 v141, v216, v140
	v_rcp_f32_e32 v135, v135
	v_mul_f32_e32 v137, 0xbfb8aa3b, v137
	v_exp_f32_e32 v137, v137
	s_waitcnt lgkmcnt(0)
	v_add_f32_e32 v140, v140, v141
	v_rcp_f32_e32 v141, v134
	v_add_f32_e32 v134, v142, v136
	v_mul_f32_e32 v134, 0xbfb8aa3b, v134
	v_exp_f32_e32 v136, v134
	v_mul_f32_e32 v135, 0xbf1b4598, v135
	v_max_f32_e32 v140, 0x179abe15, v140
	v_mul_f32_e32 v135, 0x3fb8aa3b, v135
	v_rsq_f32_e32 v134, v140
	v_add_f32_e32 v136, 1.0, v136
	v_add_f32_e32 v137, 1.0, v137
	v_exp_f32_e32 v135, v135
	v_mul_f32_e32 v140, 0xbf1b4598, v141
	v_rcp_f32_e32 v136, v136
	v_rcp_f32_e32 v137, v137
	v_mul_f32_e32 v140, 0x3fb8aa3b, v140
	v_exp_f32_e32 v140, v140
	v_pk_mul_f32 v[132:133], v[132:133], v[134:135] op_sel_hi:[1,0]
	v_add_f32_e32 v141, -1.0, v136
	v_mul_f32_e32 v134, v136, v132
	v_mul_f32_e32 v136, v137, v133
	v_add_f32_e32 v137, -1.0, v137
	v_fma_f32 v138, v138, v141, 1.0
	v_fma_f32 v137, v139, v137, 1.0
	v_mul_f32_e32 v130, v130, v138
	v_mul_f32_e32 v131, v131, v137
	ds_write2_b32 v218, v140, v135 offset1:16
	ds_write2_b32 v218, v134, v136 offset0:64 offset1:80
	ds_write2_b32 v218, v130, v131 offset0:128 offset1:144
	ds_write_b64 v219, v[132:133] offset:768
	ds_read_b64 v[130:131], v217 offset:2048
	ds_read_b64 v[132:133], v214
	ds_read_b64 v[134:135], v212
	ds_read_b64 v[136:137], v213
	ds_read_b64 v[138:139], v215
	s_waitcnt lgkmcnt(3)
	v_pk_mul_f32 v[132:133], v[132:133], v[130:131]
	s_nop 0
	v_pk_mul_f32 v[140:141], v[132:133], v[132:133]
	s_waitcnt lgkmcnt(2)
	v_add_f32_e32 v134, v155, v134
	v_add_f32_e32 v140, v140, v141
	v_add_f32_e32 v135, v147, v135
	v_mul_f32_e32 v134, 0xbfb8aa3b, v134
	v_add_f32_dpp v140, v140, v140 quad_perm:[1,0,3,2] row_mask:0xf bank_mask:0xf bound_ctrl:1
	v_mul_f32_e32 v135, 0xbfb8aa3b, v135
	v_exp_f32_e32 v134, v134
	v_add_f32_dpp v140, v140, v140 quad_perm:[2,3,0,1] row_mask:0xf bank_mask:0xf bound_ctrl:1
	v_exp_f32_e32 v135, v135
	s_waitcnt lgkmcnt(1)
	v_add_f32_e32 v137, v151, v137
	v_add_f32_dpp v140, v140, v140 row_ror:4 row_mask:0xf bank_mask:0xf bound_ctrl:1
	v_add_f32_e32 v134, 1.0, v134
	v_add_f32_e32 v135, 1.0, v135
	v_add_f32_dpp v140, v140, v140 row_ror:8 row_mask:0xf bank_mask:0xf bound_ctrl:1
	ds_bpermute_b32 v141, v216, v140
	v_rcp_f32_e32 v135, v135
	v_mul_f32_e32 v137, 0xbfb8aa3b, v137
	v_exp_f32_e32 v137, v137
	s_waitcnt lgkmcnt(0)
	v_add_f32_e32 v140, v140, v141
	v_rcp_f32_e32 v141, v134
	v_add_f32_e32 v134, v143, v136
	v_mul_f32_e32 v134, 0xbfb8aa3b, v134
	v_exp_f32_e32 v136, v134
	v_mul_f32_e32 v135, 0xbf1b4598, v135
	v_max_f32_e32 v140, 0x179abe15, v140
	v_mul_f32_e32 v135, 0x3fb8aa3b, v135
	v_rsq_f32_e32 v134, v140
	v_add_f32_e32 v136, 1.0, v136
	v_add_f32_e32 v137, 1.0, v137
	v_exp_f32_e32 v135, v135
	v_rcp_f32_e32 v136, v136
	v_rcp_f32_e32 v137, v137
	v_mul_f32_e32 v140, 0xbf1b4598, v141
	v_mul_f32_e32 v140, 0x3fb8aa3b, v140
	v_exp_f32_e32 v140, v140
	v_pk_mul_f32 v[132:133], v[132:133], v[134:135] op_sel_hi:[1,0]
	v_add_f32_e32 v141, -1.0, v136
	v_mul_f32_e32 v134, v136, v132
	v_mul_f32_e32 v136, v137, v133
	v_add_f32_e32 v137, -1.0, v137
	v_fma_f32 v137, v139, v137, 1.0
	v_fma_f32 v138, v138, v141, 1.0
	v_mul_f32_e32 v131, v131, v137
	v_add_u32_e32 v137, 0x400, v218
	v_mul_f32_e32 v130, v130, v138
	ds_write2_b32 v137, v140, v135 offset0:128 offset1:144
	ds_write2_b32 v137, v134, v136 offset0:192 offset1:208
	v_add_u32_e32 v134, 0x800, v218
	ds_write2_b32 v134, v130, v131 offset1:16
	ds_write_b64 v219, v[132:133] offset:2304
	ds_read_b64 v[130:131], v217 offset:3584
	ds_read_b64 v[132:133], v214
	ds_read_b64 v[134:135], v212
	ds_read_b64 v[136:137], v213
	ds_read_b64 v[138:139], v215
	s_waitcnt lgkmcnt(3)
	v_pk_mul_f32 v[132:133], v[132:133], v[130:131]
	s_nop 0
	v_pk_mul_f32 v[140:141], v[132:133], v[132:133]
	s_waitcnt lgkmcnt(2)
	v_add_f32_e32 v134, v156, v134
	v_add_f32_e32 v140, v140, v141
	v_add_f32_e32 v135, v148, v135
	v_mul_f32_e32 v134, 0xbfb8aa3b, v134
	v_add_f32_dpp v140, v140, v140 quad_perm:[1,0,3,2] row_mask:0xf bank_mask:0xf bound_ctrl:1
	v_mul_f32_e32 v135, 0xbfb8aa3b, v135
	v_exp_f32_e32 v134, v134
	v_add_f32_dpp v140, v140, v140 quad_perm:[2,3,0,1] row_mask:0xf bank_mask:0xf bound_ctrl:1
	v_exp_f32_e32 v135, v135
	s_waitcnt lgkmcnt(1)
	v_add_f32_e32 v137, v152, v137
	v_add_f32_dpp v140, v140, v140 row_ror:4 row_mask:0xf bank_mask:0xf bound_ctrl:1
	v_add_f32_e32 v134, 1.0, v134
	v_add_f32_e32 v135, 1.0, v135
	v_add_f32_dpp v140, v140, v140 row_ror:8 row_mask:0xf bank_mask:0xf bound_ctrl:1
	ds_bpermute_b32 v141, v216, v140
	v_rcp_f32_e32 v135, v135
	v_mul_f32_e32 v137, 0xbfb8aa3b, v137
	v_exp_f32_e32 v137, v137
	s_waitcnt lgkmcnt(0)
	v_add_f32_e32 v140, v140, v141
	v_rcp_f32_e32 v141, v134
	v_add_f32_e32 v134, v144, v136
	v_mul_f32_e32 v134, 0xbfb8aa3b, v134
	v_exp_f32_e32 v136, v134
	v_mul_f32_e32 v135, 0xbf1b4598, v135
	v_max_f32_e32 v140, 0x179abe15, v140
	v_mul_f32_e32 v135, 0x3fb8aa3b, v135
	v_rsq_f32_e32 v134, v140
	v_add_f32_e32 v136, 1.0, v136
	v_add_f32_e32 v137, 1.0, v137
	v_exp_f32_e32 v135, v135
	v_rcp_f32_e32 v136, v136
	v_rcp_f32_e32 v137, v137
	v_mul_f32_e32 v140, 0xbf1b4598, v141
	v_mul_f32_e32 v140, 0x3fb8aa3b, v140
	v_exp_f32_e32 v140, v140
	v_pk_mul_f32 v[132:133], v[132:133], v[134:135] op_sel_hi:[1,0]
	v_add_f32_e32 v141, -1.0, v136
	v_mul_f32_e32 v134, v136, v132
	v_mul_f32_e32 v136, v137, v133
	v_add_f32_e32 v137, -1.0, v137
	v_fma_f32 v137, v139, v137, 1.0
	v_fma_f32 v138, v138, v141, 1.0
	v_mul_f32_e32 v131, v131, v137
	v_add_u32_e32 v137, 0xc00, v218
	v_mul_f32_e32 v130, v130, v138
	ds_write2_b32 v137, v140, v135 offset1:16
	ds_write2_b32 v137, v134, v136 offset0:64 offset1:80
	ds_write2_b32 v137, v130, v131 offset0:128 offset1:144
	ds_write_b64 v219, v[132:133] offset:3840
	ds_read_b64 v[130:131], v217 offset:5120
	ds_read_b64 v[132:133], v214
	ds_read_b64 v[134:135], v212
	ds_read_b64 v[136:137], v213
	ds_read_b64 v[138:139], v215
	s_waitcnt lgkmcnt(3)
	v_pk_mul_f32 v[132:133], v[132:133], v[130:131]
	s_nop 0
	v_pk_mul_f32 v[140:141], v[132:133], v[132:133]
	s_waitcnt lgkmcnt(2)
	v_add_f32_e32 v134, v157, v134
	v_add_f32_e32 v140, v140, v141
	v_add_f32_e32 v135, v149, v135
	v_mul_f32_e32 v134, 0xbfb8aa3b, v134
	v_add_f32_dpp v140, v140, v140 quad_perm:[1,0,3,2] row_mask:0xf bank_mask:0xf bound_ctrl:1
	v_mul_f32_e32 v135, 0xbfb8aa3b, v135
	v_exp_f32_e32 v134, v134
	v_add_f32_dpp v140, v140, v140 quad_perm:[2,3,0,1] row_mask:0xf bank_mask:0xf bound_ctrl:1
	v_exp_f32_e32 v135, v135
	s_waitcnt lgkmcnt(1)
	v_add_f32_e32 v137, v153, v137
	v_add_f32_dpp v140, v140, v140 row_ror:4 row_mask:0xf bank_mask:0xf bound_ctrl:1
	v_add_f32_e32 v134, 1.0, v134
	v_add_f32_e32 v135, 1.0, v135
	v_add_f32_dpp v140, v140, v140 row_ror:8 row_mask:0xf bank_mask:0xf bound_ctrl:1
	ds_bpermute_b32 v141, v216, v140
	v_rcp_f32_e32 v135, v135
	v_mul_f32_e32 v137, 0xbfb8aa3b, v137
	v_exp_f32_e32 v137, v137
	s_waitcnt lgkmcnt(0)
	v_add_f32_e32 v140, v140, v141
	v_rcp_f32_e32 v141, v134
	v_add_f32_e32 v134, v145, v136
	v_mul_f32_e32 v134, 0xbfb8aa3b, v134
	v_exp_f32_e32 v136, v134
	v_mul_f32_e32 v135, 0xbf1b4598, v135
	v_max_f32_e32 v140, 0x179abe15, v140
	v_mul_f32_e32 v135, 0x3fb8aa3b, v135
	v_rsq_f32_e32 v134, v140
	v_add_f32_e32 v136, 1.0, v136
	v_add_f32_e32 v137, 1.0, v137
	v_exp_f32_e32 v135, v135
	v_rcp_f32_e32 v136, v136
	v_rcp_f32_e32 v137, v137
	v_mul_f32_e32 v140, 0xbf1b4598, v141
	v_mul_f32_e32 v140, 0x3fb8aa3b, v140
	v_exp_f32_e32 v140, v140
	v_pk_mul_f32 v[132:133], v[132:133], v[134:135] op_sel_hi:[1,0]
	v_add_f32_e32 v141, -1.0, v136
	v_mul_f32_e32 v134, v136, v132
	v_mul_f32_e32 v136, v137, v133
	v_add_f32_e32 v137, -1.0, v137
	v_fma_f32 v137, v139, v137, 1.0
	v_fma_f32 v138, v138, v141, 1.0
	v_mul_f32_e32 v131, v131, v137
	v_add_u32_e32 v137, 0x1000, v218
	v_mul_f32_e32 v130, v130, v138
	ds_write2_b32 v137, v140, v135 offset0:128 offset1:144
	ds_write2_b32 v137, v134, v136 offset0:192 offset1:208
	v_add_u32_e32 v134, 0x1400, v218
	ds_write2_b32 v134, v130, v131 offset1:16
	ds_write_b64 v219, v[132:133] offset:5376
	s_setprio 2
	s_add_i32 s20, s20, 1
	s_min_u32 s12, s20, 25
	s_lshl_b32 s12, s12, 3
	s_add_i32 s12, s12, s1
	s_cmpk_gt_i32 s12, 0xff
	s_mov_b64 s[14:15], -1
	s_cbranch_scc0 .LBB0_360
	s_and_b64 vcc, exec, s[4:5]
	s_cbranch_vccnz .LBB0_357
	s_sub_i32 s21, 0x40ff, s12
	s_mov_b64 s[14:15], 0

.LBB0_710:
	s_add_i32 s23, s22, -7
	s_and_b64 s[20:21], s[2:3], exec
	s_cselect_b32 s39, s22, s23
	s_add_i32 s20, s39, -1
	s_max_i32 s20, s20, s38
	s_min_i32 s20, s20, s37
	s_mulk_i32 s20, 0x1800
	s_add_u32 s20, s88, s20
	s_addc_u32 s21, s89, 0
	s_max_i32 s22, s39, s38
	s_min_i32 s22, s22, s37
	s_mulk_i32 s22, 0x1800
	s_add_u32 s22, s88, s22
	s_addc_u32 s23, s89, 0
	s_add_i32 s24, s39, 1
	s_max_i32 s24, s24, s38
	s_min_i32 s24, s24, s37
	s_mulk_i32 s24, 0x1800
	s_add_u32 s24, s88, s24
	s_addc_u32 s25, s89, 0
	s_add_i32 s26, s39, 2
	s_max_i32 s26, s26, s38
	s_min_i32 s26, s26, s37
	s_mulk_i32 s26, 0x1800
	s_add_u32 s26, s88, s26
	s_addc_u32 s27, s89, 0
	s_add_i32 s28, s39, 3
	s_max_i32 s28, s28, s38
	s_min_i32 s28, s28, s37
	s_mulk_i32 s28, 0x1800
	s_add_u32 s28, s88, s28
	s_addc_u32 s29, s89, 0
	s_add_i32 s40, s39, 4
	s_max_i32 s40, s40, s38
	s_min_i32 s40, s40, s37
	s_mulk_i32 s40, 0x1800
	s_add_u32 s40, s88, s40
	s_addc_u32 s41, s89, 0
	s_add_i32 s42, s39, 5
	s_max_i32 s42, s42, s38
	s_min_i32 s42, s42, s37
	s_mulk_i32 s42, 0x1800
	s_add_u32 s42, s88, s42
	s_addc_u32 s43, s89, 0
	s_add_i32 s44, s39, 6
	s_max_i32 s44, s44, s38
	s_min_i32 s44, s44, s37
	s_mulk_i32 s44, 0x1800
	s_add_u32 s44, s88, s44
	s_addc_u32 s45, s89, 0
	s_add_i32 s46, s39, 7
	s_max_i32 s46, s46, s38
	s_min_i32 s46, s46, s37
	s_mulk_i32 s46, 0x1800
	s_add_u32 s46, s88, s46
	s_addc_u32 s47, s89, 0
	s_add_i32 s39, s39, 8
	s_max_i32 s39, s39, s38
	s_min_i32 s39, s39, s37
	s_mulk_i32 s39, 0x1800
	v_lshl_add_u64 v[68:69], s[22:23], 0, v[148:149]
	s_add_u32 s48, s88, s39
	v_lshl_add_u64 v[66:67], s[20:21], 0, v[148:149]
	v_lshl_add_u64 v[70:71], s[24:25], 0, v[148:149]
	v_lshl_add_u64 v[72:73], s[26:27], 0, v[148:149]
	v_lshl_add_u64 v[74:75], s[28:29], 0, v[148:149]
	global_load_ushort v97, v[68:69], off offset:1536
	global_load_ushort v93, v[68:69], off offset:3072
	global_load_ushort v98, v[70:71], off offset:1536
	global_load_ushort v94, v[70:71], off offset:3072
	global_load_ushort v96, v[72:73], off offset:1536
	global_load_ushort v81, v[72:73], off offset:3072
	global_load_ushort v95, v[74:75], off offset:1536
	global_load_ushort v80, v[74:75], off offset:3072
	v_lshl_add_u64 v[68:69], s[40:41], 0, v[148:149]
	s_addc_u32 s49, s89, 0
	v_lshl_add_u64 v[70:71], s[42:43], 0, v[148:149]
	global_load_ushort v115, v218, s[20:21]
	global_load_ushort v112, v218, s[22:23]
	global_load_ushort v113, v218, s[24:25]
	global_load_ushort v110, v218, s[26:27]
	global_load_ushort v109, v218, s[28:29]
	global_load_ushort v108, v218, s[40:41]
	global_load_ushort v107, v218, s[42:43]
	global_load_ushort v105, v218, s[44:45]
	v_lshl_add_u64 v[72:73], s[44:45], 0, v[148:149]
	v_lshl_add_u64 v[74:75], s[46:47], 0, v[148:149]
	global_load_ushort v104, v[68:69], off offset:1536
	global_load_ushort v91, v[68:69], off offset:3072
	global_load_ushort v102, v[70:71], off offset:1536
	global_load_ushort v90, v[70:71], off offset:3072
	global_load_ushort v101, v[72:73], off offset:1536
	global_load_ushort v89, v[72:73], off offset:3072
	global_load_ushort v100, v[74:75], off offset:1536
	global_load_ushort v88, v[74:75], off offset:3072
	global_load_ushort v106, v[66:67], off offset:1536
	global_load_ushort v99, v[66:67], off offset:3072
	global_load_ushort v85, v219, s[20:21]
	global_load_ushort v86, v219, s[22:23]
	global_load_ushort v87, v219, s[24:25]
	global_load_ushort v84, v219, s[26:27]
	global_load_ushort v114, v218, s[46:47]
	global_load_ushort v111, v218, s[48:49]
	v_lshl_add_u64 v[66:67], s[48:49], 0, v[148:149]
	global_load_ushort v103, v[66:67], off offset:1536
	global_load_ushort v92, v[66:67], off offset:3072
	global_load_ushort v73, v220, s[20:21]
	global_load_ushort v74, v220, s[22:23]
	global_load_ushort v83, v219, s[28:29]
	global_load_ushort v82, v219, s[40:41]
	global_load_ushort v79, v219, s[42:43]
	global_load_ushort v78, v219, s[44:45]
	global_load_ushort v77, v219, s[46:47]
	global_load_ushort v76, v219, s[48:49]
	global_load_ushort v75, v220, s[24:25]
	global_load_ushort v72, v220, s[26:27]
	global_load_ushort v71, v220, s[28:29]
	global_load_ushort v70, v220, s[40:41]
	global_load_ushort v69, v220, s[42:43]
	global_load_ushort v68, v220, s[44:45]
	global_load_ushort v67, v220, s[46:47]
	global_load_ushort v66, v220, s[48:49]
	s_setprio 0
	s_mov_b64 s[20:21], -1
	s_and_b64 vcc, exec, s[18:19]
	s_cbranch_vccz .LBB0_716
	s_and_b64 vcc, exec, s[8:9]
	s_mov_b64 s[8:9], -1
	s_cbranch_vccnz .LBB0_713
	s_sub_i32 s18, 0x40ff, s36
	s_mov_b64 s[8:9], 0

.LBB0_728:
	s_or_b64 exec, exec, s[8:9]
	s_setprio 2
	s_waitcnt lgkmcnt(0)
	v_and_b32_e32 v108, 15, v1
	v_lshrrev_b32_e32 v109, 4, v1
	v_lshl_add_u32 v108, v108, 2, v109
	v_lshl_add_u32 v66, v108, 2, s30
	v_lshl_add_u32 v67, v1, 2, s30
	ds_read_b32 v68, v67 offset:0
	ds_read_b32 v71, v66 offset:768
	ds_read_b32 v69, v67 offset:256
	ds_read_b32 v70, v67 offset:512
	ds_read_b32 v72, v66 offset:1024
	ds_read_b32 v73, v67 offset:1536
	ds_read_b32 v76, v66 offset:2304
	ds_read_b32 v74, v67 offset:1792
	ds_read_b32 v75, v67 offset:2048
	ds_read_b32 v77, v66 offset:2560
	ds_read_b32 v78, v67 offset:3072
	ds_read_b32 v81, v66 offset:3840
	ds_read_b32 v79, v67 offset:3328
	ds_read_b32 v80, v67 offset:3584
	ds_read_b32 v82, v66 offset:4096
	ds_read_b32 v83, v67 offset:4608
	ds_read_b32 v86, v66 offset:5376
	ds_read_b32 v84, v67 offset:4864
	ds_read_b32 v85, v67 offset:5120
	ds_read_b32 v87, v66 offset:5632
	ds_read_b32 v88, v67 offset:6144
	ds_read_b32 v91, v66 offset:6912
	ds_read_b32 v89, v67 offset:6400
	ds_read_b32 v90, v67 offset:6656
	ds_read_b32 v92, v66 offset:7168
	ds_read_b32 v93, v67 offset:7680
	ds_read_b32 v96, v66 offset:8448
	ds_read_b32 v94, v67 offset:7936
	ds_read_b32 v95, v67 offset:8192
	ds_read_b32 v97, v66 offset:8704
	ds_read_b32 v98, v67 offset:9216
	ds_read_b32 v101, v66 offset:9984
	ds_read_b32 v99, v67 offset:9472
	ds_read_b32 v100, v67 offset:9728
	ds_read_b32 v102, v66 offset:10240
	ds_read_b32 v103, v67 offset:10752
	ds_read_b32 v106, v66 offset:11520
	ds_read_b32 v104, v67 offset:11008
	ds_read_b32 v105, v67 offset:11264
	ds_read_b32 v107, v66 offset:11776
	v_and_b32_e32 v118, 31, v1
	v_lshrrev_b32_e32 v119, 5, v1
	v_lshlrev_b32_e32 v240, 4, v119
	v_lshlrev_b32_e32 v120, 8, v119
	v_lshl_add_u32 v241, v118, 2, v120
	v_add_u32_e32 v241, 0x100, v241
	v_lshlrev_b32_e32 v121, 2, v118
	v_sub_u32_e32 v242, v121, v120
	v_add_u32_e32 v242, 0x200, v242
	v_xor_b32_e32 v121, 32, v1
	v_lshlrev_b32_e32 v121, 2, v121
	v_add_u32_e32 v243, 0x500, v121
	s_mov_b32 s98, 0
	s_mov_b32 s99, -1
	s_waitcnt lgkmcnt(0)
	v_rcp_f32_e32 v111, v68
	v_mov_b32_e32 v110, v68
	v_mul_f32_e32 v72, v72, v110
	v_mul_f32_e32 v69, v69, v111
	v_mul_f32_e32 v70, v70, v111
	ds_write_b32 v67, v71 offset:768
	ds_write_b32 v67, v72 offset:1024
	ds_write_b32 v67, v69 offset:256
	ds_write_b32 v67, v70 offset:512
	v_mul_f32_e32 v76, v76, v110
	v_mul_f32_e32 v110, v110, v73
	v_rcp_f32_e32 v111, v110
	v_mul_f32_e32 v77, v77, v110
	v_mul_f32_e32 v74, v74, v111
	v_mul_f32_e32 v75, v75, v111
	ds_write_b32 v67, v76 offset:2304
	ds_write_b32 v67, v77 offset:2560
	ds_write_b32 v67, v74 offset:1792
	ds_write_b32 v67, v75 offset:2048
	v_mul_f32_e32 v81, v81, v110
	v_mul_f32_e32 v110, v110, v78
	v_rcp_f32_e32 v111, v110
	v_mul_f32_e32 v82, v82, v110
	v_mul_f32_e32 v79, v79, v111
	v_mul_f32_e32 v80, v80, v111
	ds_write_b32 v67, v81 offset:3840
	ds_write_b32 v67, v82 offset:4096
	ds_write_b32 v67, v79 offset:3328
	ds_write_b32 v67, v80 offset:3584
	v_mul_f32_e32 v86, v86, v110
	v_mul_f32_e32 v110, v110, v83
	v_rcp_f32_e32 v111, v110
	v_mul_f32_e32 v87, v87, v110
	v_mul_f32_e32 v84, v84, v111
	v_mul_f32_e32 v85, v85, v111
	ds_write_b32 v67, v86 offset:5376
	ds_write_b32 v67, v87 offset:5632
	ds_write_b32 v67, v84 offset:4864
	ds_write_b32 v67, v85 offset:5120
	v_mul_f32_e32 v91, v91, v110
	v_mul_f32_e32 v110, v110, v88
	v_rcp_f32_e32 v111, v110
	v_mul_f32_e32 v92, v92, v110
	v_mul_f32_e32 v89, v89, v111
	v_mul_f32_e32 v90, v90, v111
	ds_write_b32 v67, v91 offset:6912
	ds_write_b32 v67, v92 offset:7168
	ds_write_b32 v67, v89 offset:6400
	ds_write_b32 v67, v90 offset:6656
	v_mul_f32_e32 v96, v96, v110
	v_mul_f32_e32 v110, v110, v93
	v_rcp_f32_e32 v111, v110
	v_mul_f32_e32 v97, v97, v110
	v_mul_f32_e32 v94, v94, v111
	v_mul_f32_e32 v95, v95, v111
	ds_write_b32 v67, v96 offset:8448
	ds_write_b32 v67, v97 offset:8704
	ds_write_b32 v67, v94 offset:7936
	ds_write_b32 v67, v95 offset:8192
	v_mul_f32_e32 v101, v101, v110
	v_mul_f32_e32 v110, v110, v98
	v_rcp_f32_e32 v111, v110
	v_mul_f32_e32 v102, v102, v110
	v_mul_f32_e32 v99, v99, v111
	v_mul_f32_e32 v100, v100, v111
	ds_write_b32 v67, v101 offset:9984
	ds_write_b32 v67, v102 offset:10240
	ds_write_b32 v67, v99 offset:9472
	ds_write_b32 v67, v100 offset:9728
	v_mul_f32_e32 v106, v106, v110
	v_mul_f32_e32 v110, v110, v103
	v_rcp_f32_e32 v111, v110
	v_mul_f32_e32 v107, v107, v110
	v_mul_f32_e32 v104, v104, v111
	v_mul_f32_e32 v105, v105, v111
	ds_write_b32 v67, v106 offset:11520
	ds_write_b32 v67, v107 offset:11776
	ds_write_b32 v67, v104 offset:11008
	ds_write_b32 v67, v105 offset:11264
	ds_write_b32 v67, v110
	v_add_u32_e32 v229, s30, v240
	s_waitcnt lgkmcnt(0)
	ds_read_b128 v[66:69], v229 offset:768
	ds_read_b128 v[70:73], v229 offset:800
	ds_read_b128 v[74:77], v229 offset:832
	ds_read_b128 v[78:81], v229 offset:864
	ds_read_b128 v[82:85], v229 offset:896
	ds_read_b128 v[86:89], v229 offset:928
	ds_read_b128 v[90:93], v229 offset:960
	ds_read_b128 v[94:97], v229 offset:992
	s_mov_b32 s8, 8
	s_mov_b32 s9, s30
	s_mov_b32 s18, s12
